# general (diagonal) tile loops: next tile's V^T fragment reads moved into the previous K.Q^T block as in the fast loops; explicit reads at the loop entry
# speedup vs baseline: 1.0065x; 1.0065x over previous
; #define ATT_BAR() do { asm volatile("s_waitcnt lgkmcnt(0)" ::: "memory"); __builtin_amdgcn_s_barrier(); asm volatile("" ::: "memory"); } while (0)
; template <int DK, int DV>
; __device__ __forceinline__ void attn_unit(LAS unsigned char* lds, const bf16* Qp, int ldq, const bf16* Kp, int ldk, const bf16* VTp, bf16* Op, int ldo, int qb) {
;     ...
;     ATT_LOAD(0, kra, vra); ATT_LOAD(1, krb, vrb);
;     ATT_STORE(0, kra, vra); ATT_STORE(BUF, krb, vrb);
;     ATT_LOAD(2, krb, vrb);
;     __syncthreads();
;     float mrun = 0.f, lrun = 0.f;
;     f32x16 o[NDB];
; #pragma unroll
;     for (int db = 0; db < NDB; ++db)
; #pragma unroll
;         for (int r = 0; r < 16; ++r) o[db][r] = 0.f;
;     f32x16 s0, s1;
;     const f32x16 zacc = {0.f, 0.f, 0.f, 0.f, 0.f, 0.f, 0.f, 0.f, 0.f, 0.f, 0.f, 0.f, 0.f, 0.f, 0.f, 0.f};
;     f32x16 negm = zacc;
;     constexpr float ATT_THR = 8.f;
;     ATT_QK(0, zacc);
;     if (grpB) ATT_BAR();
;     int bcur = 0, bnext = BUF, bfree = 2 * BUF;
; #pragma unroll 1
;     for (int t = 0; t < NT; t += 2) {
.LBB0_1036:
	ds_read_b128 v[196:199], v141
	ds_read_b128 v[200:203], v141 offset:1024
	ds_read_b128 v[204:207], v141 offset:2048
	ds_read_b128 v[208:211], v141 offset:3072
	ds_read_b128 v[212:215], v141 offset:4096
	ds_read_b128 v[216:219], v141 offset:5120
	v_or_b32_e32 v159, s46, v6
	v_mul_u32_u24_e32 v6, 0x90, v6
	v_lshlrev_b32_e32 v158, 2, v7
	v_lshl_add_u64 v[144:145], v[2:3], 1, s[4:5]
	v_lshl_add_u64 v[146:147], v[4:5], 1, s[4:5]
	v_mad_i64_i32 v[186:187], vcc, v150, s3, v[144:145]
	v_mad_i64_i32 v[188:189], vcc, v151, s3, v[146:147]
	v_add3_u32 v160, 0, v6, v0
	v_mov_b32_e32 v2, v1
	v_mov_b32_e32 v3, v1
	v_mov_b32_e32 v4, v1
	v_mov_b32_e32 v5, v1
	v_mov_b32_e32 v6, v1
	v_mov_b32_e32 v7, v1
	v_mov_b32_e32 v8, v1
	v_mov_b32_e32 v9, v1
	v_mov_b32_e32 v10, v1
	v_mov_b32_e32 v11, v1
	v_mov_b32_e32 v12, v1
	v_mov_b32_e32 v13, v1
	v_mov_b32_e32 v14, v1
	v_mov_b32_e32 v15, v1
	v_mov_b32_e32 v16, v1
	v_mov_b32_e32 v17, v1
	v_mov_b32_e32 v18, v1
	v_mov_b32_e32 v19, v1
	v_mov_b32_e32 v20, v1
	v_mov_b32_e32 v21, v1
	v_mov_b32_e32 v22, v1
	v_mov_b32_e32 v23, v1
	v_mov_b32_e32 v24, v1
	v_mov_b32_e32 v25, v1
	v_mov_b32_e32 v26, v1
	v_mov_b32_e32 v27, v1
	v_mov_b32_e32 v28, v1
	v_mov_b32_e32 v29, v1
	v_mov_b32_e32 v30, v1
	v_mov_b32_e32 v31, v1
	s_lshl_b32 s48, s0, 2
	v_mov_b32_e32 v0, v1
	v_mov_b64_e32 v[32:33], v[30:31]
	s_lshl_b32 s47, s1, 13
	v_ashrrev_i32_e32 v139, 31, v138
	s_add_i32 s49, s48, 4
	s_or_b32 s50, s48, 3
	s_or_b32 s51, s46, 31
	s_mov_b32 s54, 0
	s_sub_i32 s55, 0, s48
	s_sub_i32 s56, 0, s8
	v_subrev_u32_e32 v161, s8, v158
	v_mov_b32_e32 v66, v1
	v_mov_b32_e32 v67, v1
	v_mov_b32_e32 v68, v1
	v_mov_b32_e32 v69, v1
	v_mov_b32_e32 v70, v1
	v_mov_b32_e32 v71, v1
	v_mov_b32_e32 v72, v1
	v_mov_b32_e32 v73, v1
	v_mov_b32_e32 v74, v1
	v_mov_b32_e32 v75, v1
	v_mov_b32_e32 v76, v1
	v_mov_b32_e32 v77, v1
	v_mov_b32_e32 v78, v1
	v_mov_b32_e32 v79, v1
	v_mov_b32_e32 v80, v1
	v_mov_b32_e32 v81, v1
	s_mov_b32 s57, 0xb000
	s_movk_i32 s58, 0x5800
	v_mov_b32_e32 v162, 0
	v_mov_b32_e32 v163, 0
	s_mov_b32 s0, 0
	s_mov_b32 s59, 0
	v_mov_b64_e32 v[30:31], v[28:29]
	v_mov_b64_e32 v[28:29], v[26:27]
	v_mov_b64_e32 v[26:27], v[24:25]
	v_mov_b64_e32 v[24:25], v[22:23]
	v_mov_b64_e32 v[22:23], v[20:21]
	v_mov_b64_e32 v[20:21], v[18:19]
	v_mov_b64_e32 v[18:19], v[16:17]
	v_mov_b64_e32 v[16:17], v[14:15]
	v_mov_b64_e32 v[14:15], v[12:13]
	v_mov_b64_e32 v[12:13], v[10:11]
	v_mov_b64_e32 v[10:11], v[8:9]
	v_mov_b64_e32 v[8:9], v[6:7]
	v_mov_b64_e32 v[6:7], v[4:5]
	v_mov_b64_e32 v[4:5], v[2:3]
	v_mov_b64_e32 v[2:3], v[0:1]
	s_add_i32 s1, s59, 3
	s_cmp_lt_u32 s1, s49
	s_cselect_b32 s1, s1, s50
	s_lshl_b32 s8, s1, 6
	s_mul_i32 s4, s8, 0x600
	s_mov_b32 s5, 0
	v_lshl_add_u64 v[94:95], s[4:5], 0, v[186:187]
	v_lshl_add_u64 v[96:97], s[4:5], 0, v[188:189]
	v_lshl_add_u64 v[102:103], s[8:9], 1, v[142:143]
	global_load_dwordx4 v[98:101], v[94:95], off
	s_nop 0
	global_load_dwordx4 v[94:97], v[96:97], off
	global_load_dwordx4 v[102:105], v[102:103], off
	s_add_i32 s4, s55, s59
	s_cmp_lt_i32 s4, -1
	s_cbranch_scc1 .Lfm_entry
	v_add_u32_e32 v248, s0, v160
	ds_read_b128 v[164:167], v248 offset:13312
	ds_read_b128 v[168:171], v248 offset:17920
	ds_read_b128 v[172:175], v248 offset:13344
	ds_read_b128 v[176:179], v248 offset:17952
	ds_read_b128 v[180:183], v248 offset:13376
	ds_read_b128 v[220:223], v248 offset:17984
	ds_read_b128 v[224:227], v248 offset:13408
	ds_read_b128 v[232:235], v248 offset:18016
.LBB0_1037:
	s_add_i32 s62, s55, s59
	s_cmp_lt_i32 s62, 0
	s_cselect_b64 s[18:19], -1, 0
	s_add_i32 s61, s56, s54
	s_cmp_le_i32 s61, s51
	s_cselect_b64 s[4:5], -1, 0
	s_or_b64 s[20:21], s[18:19], s[4:5]
	s_mov_b32 s60, s58
	s_not_b64 s[4:5], s[20:21]
	s_andn2_b64 vcc, exec, s[20:21]
	s_mov_b32 s58, s0
	s_cbranch_vccnz .LBB0_1049
	s_cmp_lt_i32 s62, 0
	s_cbranch_scc0 .Lmla_a_mask

.LBB0_1051:
	s_add_i32 s0, s59, 1
	s_cmp_lt_u32 s0, s49
	s_cselect_b64 s[0:1], -1, 0
	s_add_i32 s4, s61, 33
	s_cmp_le_i32 s4, s46
	s_cselect_b64 s[4:5], -1, 0
	s_or_b64 s[4:5], s[18:19], s[4:5]
	s_and_b64 s[0:1], s[0:1], s[4:5]
	s_andn2_b64 vcc, exec, s[0:1]
	s_cbranch_vccnz .LBB0_1053
	s_waitcnt lgkmcnt(5)
	v_mfma_f32_32x32x16_bf16 v[34:49], v[236:239], v[196:199], v[66:81]
	ds_read_b128 v[236:239], v249 offset:6816
	v_mfma_f32_32x32x16_bf16 v[50:65], v[240:243], v[196:199], v[66:81]
	v_mfma_f32_32x32x16_bf16 v[34:49], v[244:247], v[200:203], v[34:49]
	v_add_u32_e32 v248, s60, v160
	v_mfma_f32_32x32x16_bf16 v[50:65], v[164:167], v[200:203], v[50:65]
	ds_read_b128 v[164:167], v248 offset:13312
	v_mfma_f32_32x32x16_bf16 v[34:49], v[168:171], v[204:207], v[34:49]
	ds_read_b128 v[168:171], v248 offset:17920
	v_mfma_f32_32x32x16_bf16 v[50:65], v[172:175], v[204:207], v[50:65]
	ds_read_b128 v[172:175], v248 offset:13344
	s_waitcnt lgkmcnt(4)
	v_mfma_f32_32x32x16_bf16 v[34:49], v[176:179], v[208:211], v[34:49]
	ds_read_b128 v[176:179], v248 offset:17952
	v_mfma_f32_32x32x16_bf16 v[50:65], v[180:183], v[208:211], v[50:65]
	ds_read_b128 v[180:183], v248 offset:13376
	v_mfma_f32_32x32x16_bf16 v[34:49], v[220:223], v[212:215], v[34:49]
	ds_read_b128 v[220:223], v248 offset:17984
	v_mfma_f32_32x32x16_bf16 v[50:65], v[224:227], v[212:215], v[50:65]
	ds_read_b128 v[224:227], v248 offset:13408
	v_mfma_f32_32x32x16_bf16 v[34:49], v[232:235], v[216:219], v[34:49]
	ds_read_b128 v[232:235], v248 offset:18016
	s_waitcnt lgkmcnt(8)
	v_mfma_f32_32x32x16_bf16 v[50:65], v[236:239], v[216:219], v[50:65]
.LBB0_1053:
	s_setprio 0
	s_add_i32 s0, s59, 4
	s_cmp_lt_u32 s59, s48
	s_cselect_b32 s0, s0, s50
	s_lshl_b32 s8, s0, 6
	s_mul_i32 s0, s8, 0x600
	s_mov_b32 s1, 0
	v_lshl_add_u64 v[82:83], s[0:1], 0, v[186:187]
	v_lshl_add_u64 v[84:85], s[0:1], 0, v[188:189]
	global_load_dwordx4 v[86:89], v[82:83], off
	global_load_dwordx4 v[90:93], v[84:85], off
	v_lshl_add_u64 v[82:83], s[8:9], 1, v[142:143]
	global_load_dwordx4 v[82:85], v[82:83], off
	s_waitcnt lgkmcnt(8)
	s_barrier
	s_add_i32 s62, s62, 1
	s_cmp_lt_i32 s62, 0
	s_cselect_b64 s[0:1], -1, 0
	s_add_i32 s4, s61, 64
	s_cmp_le_i32 s4, s51
	s_cselect_b64 s[4:5], -1, 0
	s_or_b64 s[0:1], s[0:1], s[4:5]
	s_not_b64 s[4:5], s[0:1]
	s_andn2_b64 vcc, exec, s[0:1]
	s_cbranch_vccnz .LBB0_1059
	s_cmp_lt_i32 s62, 0
	s_cbranch_scc0 .Lmla_b_mask

.LBB0_1061:
	s_add_i32 s59, s59, 2
	s_cmp_ge_u32 s59, s49
	s_cselect_b64 s[4:5], -1, 0
	s_cmp_lt_u32 s59, s49
	s_cselect_b64 s[0:1], -1, 0
	s_cmp_lt_i32 s62, -1
	s_cselect_b64 s[18:19], -1, 0
	s_addk_i32 s61, 0x61
	s_cmp_le_i32 s61, s46
	s_cselect_b64 s[20:21], -1, 0
	s_or_b64 s[18:19], s[18:19], s[20:21]
	s_and_b64 s[0:1], s[0:1], s[18:19]
	s_andn2_b64 vcc, exec, s[0:1]
	s_cbranch_vccnz .LBB0_1063
	s_waitcnt lgkmcnt(5)
	v_mfma_f32_32x32x16_bf16 v[34:49], v[236:239], v[196:199], v[66:81]
	ds_read_b128 v[236:239], v249 offset:6816
	v_mfma_f32_32x32x16_bf16 v[50:65], v[240:243], v[196:199], v[66:81]
	v_mfma_f32_32x32x16_bf16 v[34:49], v[244:247], v[200:203], v[34:49]
	v_add_u32_e32 v248, s57, v160
	v_mfma_f32_32x32x16_bf16 v[50:65], v[164:167], v[200:203], v[50:65]
	ds_read_b128 v[164:167], v248 offset:13312
	v_mfma_f32_32x32x16_bf16 v[34:49], v[168:171], v[204:207], v[34:49]
	ds_read_b128 v[168:171], v248 offset:17920
	v_mfma_f32_32x32x16_bf16 v[50:65], v[172:175], v[204:207], v[50:65]
	ds_read_b128 v[172:175], v248 offset:13344
	s_waitcnt lgkmcnt(4)
	v_mfma_f32_32x32x16_bf16 v[34:49], v[176:179], v[208:211], v[34:49]
	ds_read_b128 v[176:179], v248 offset:17952
	v_mfma_f32_32x32x16_bf16 v[50:65], v[180:183], v[208:211], v[50:65]
	ds_read_b128 v[180:183], v248 offset:13376
	v_mfma_f32_32x32x16_bf16 v[34:49], v[220:223], v[212:215], v[34:49]
	ds_read_b128 v[220:223], v248 offset:17984
	v_mfma_f32_32x32x16_bf16 v[50:65], v[224:227], v[212:215], v[50:65]
	ds_read_b128 v[224:227], v248 offset:13408
	v_mfma_f32_32x32x16_bf16 v[34:49], v[232:235], v[216:219], v[34:49]
	ds_read_b128 v[232:235], v248 offset:18016
	s_waitcnt lgkmcnt(8)
	v_mfma_f32_32x32x16_bf16 v[50:65], v[236:239], v[216:219], v[50:65]

.Lmla_b_nold:
	s_waitcnt lgkmcnt(8)
	s_barrier
	s_addk_i32 s54, 0x80
	s_and_b64 vcc, exec, s[4:5]
	s_cbranch_vccnz .LBB0_1065
	s_mov_b32 s0, s57
	s_mov_b32 s57, s60
	s_branch .LBB0_1037

; #define ATT_BAR() do { asm volatile("s_waitcnt lgkmcnt(0)" ::: "memory"); __builtin_amdgcn_s_barrier(); asm volatile("" ::: "memory"); } while (0)
; template <int DK, int DV>
; __device__ __forceinline__ void attn_unit(LAS unsigned char* lds, const bf16* Qp, int ldq, const bf16* Kp, int ldk, const bf16* VTp, bf16* Op, int ldo, int qb) {
;     ...
;     ATT_LOAD(0, kra, vra); ATT_LOAD(1, krb, vrb);
;     ATT_STORE(0, kra, vra); ATT_STORE(BUF, krb, vrb);
;     ATT_LOAD(2, krb, vrb);
;     __syncthreads();
;     float mrun = 0.f, lrun = 0.f;
;     f32x16 o[NDB];
; #pragma unroll
;     for (int db = 0; db < NDB; ++db)
; #pragma unroll
;         for (int r = 0; r < 16; ++r) o[db][r] = 0.f;
;     f32x16 s0, s1;
;     const f32x16 zacc = {0.f, 0.f, 0.f, 0.f, 0.f, 0.f, 0.f, 0.f, 0.f, 0.f, 0.f, 0.f, 0.f, 0.f, 0.f, 0.f};
;     f32x16 negm = zacc;
;     constexpr float ATT_THR = 8.f;
;     ATT_QK(0, zacc);
;     if (grpB) ATT_BAR();
;     int bcur = 0, bnext = BUF, bfree = 2 * BUF;
; #pragma unroll 1
;     for (int t = 0; t < NT; t += 2) {
.LBB0_1071:
	ds_read_b128 v[232:235], v189
	ds_read_b128 v[236:239], v189 offset:1024
	ds_read_b128 v[240:243], v189 offset:2048
	ds_read_b128 v[244:247], v189 offset:3072
	v_mov_b32_e32 v14, v1
	v_mov_b32_e32 v15, v1
	s_lshl_b32 s43, s1, 2
	v_lshl_add_u64 v[182:183], v[2:3], 1, s[4:5]
	v_or_b32_e32 v192, s35, v4
	v_lshlrev_b32_e32 v191, 2, v5
	v_mov_b32_e32 v0, v1
	v_mov_b32_e32 v2, v1
	v_mov_b32_e32 v3, v1
	v_mov_b32_e32 v4, v1
	v_mov_b32_e32 v5, v1
	v_mov_b32_e32 v6, v1
	v_mov_b32_e32 v7, v1
	v_mov_b32_e32 v8, v1
	v_mov_b32_e32 v9, v1
	v_mov_b32_e32 v10, v1
	v_mov_b32_e32 v11, v1
	v_mov_b32_e32 v12, v1
	v_mov_b32_e32 v13, v1
	v_mov_b64_e32 v[30:31], v[14:15]
	v_mov_b64_e32 v[46:47], v[14:15]
	v_mov_b64_e32 v[62:63], v[14:15]
	v_mov_b64_e32 v[78:79], v[14:15]
	v_mov_b64_e32 v[126:127], v[14:15]
	s_lshl_b32 s42, s0, 13
	s_add_i32 s44, s43, 4
	s_or_b32 s45, s43, 3
	s_or_b32 s46, s35, 31
	s_mov_b32 s47, 0
	s_sub_i32 s48, 0, s43
	s_sub_i32 s49, 0, s8
	v_subrev_u32_e32 v194, s8, v191
	s_mov_b32 s50, 0xd800
	s_movk_i32 s51, 0x6c00
	v_mov_b32_e32 v193, 0
	v_mov_b64_e32 v[28:29], v[12:13]
	v_mov_b64_e32 v[26:27], v[10:11]
	v_mov_b64_e32 v[24:25], v[8:9]
	v_mov_b64_e32 v[22:23], v[6:7]
	v_mov_b64_e32 v[20:21], v[4:5]
	v_mov_b64_e32 v[18:19], v[2:3]
	v_mov_b64_e32 v[16:17], v[0:1]
	v_mov_b64_e32 v[44:45], v[12:13]
	v_mov_b64_e32 v[42:43], v[10:11]
	v_mov_b64_e32 v[40:41], v[8:9]
	v_mov_b64_e32 v[38:39], v[6:7]
	v_mov_b64_e32 v[36:37], v[4:5]
	v_mov_b64_e32 v[34:35], v[2:3]
	v_mov_b64_e32 v[32:33], v[0:1]
	v_mov_b64_e32 v[60:61], v[12:13]
	v_mov_b64_e32 v[58:59], v[10:11]
	v_mov_b64_e32 v[56:57], v[8:9]
	v_mov_b64_e32 v[54:55], v[6:7]
	v_mov_b64_e32 v[52:53], v[4:5]
	v_mov_b64_e32 v[50:51], v[2:3]
	v_mov_b64_e32 v[48:49], v[0:1]
	v_mov_b64_e32 v[76:77], v[12:13]
	v_mov_b64_e32 v[74:75], v[10:11]
	v_mov_b64_e32 v[72:73], v[8:9]
	v_mov_b64_e32 v[70:71], v[6:7]
	v_mov_b64_e32 v[68:69], v[4:5]
	v_mov_b64_e32 v[66:67], v[2:3]
	v_mov_b64_e32 v[64:65], v[0:1]
	v_mov_b32_e32 v195, 0
	v_mov_b64_e32 v[124:125], v[12:13]
	v_mov_b64_e32 v[122:123], v[10:11]
	v_mov_b64_e32 v[120:121], v[8:9]
	v_mov_b64_e32 v[118:119], v[6:7]
	v_mov_b64_e32 v[116:117], v[4:5]
	v_mov_b64_e32 v[114:115], v[2:3]
	v_mov_b64_e32 v[112:113], v[0:1]
	s_mov_b32 s0, 0
	s_mov_b32 s54, 0
	s_add_i32 s1, s54, 3
	s_cmp_lt_u32 s1, s44
	s_cselect_b32 s1, s1, s45
	s_lshl_b32 s8, s1, 6
	v_add_u32_e32 v2, s8, v174
	v_ashrrev_i32_e32 v3, 31, v2
	v_lshlrev_b64 v[2:3], 10, v[2:3]
	v_lshl_add_u64 v[6:7], s[8:9], 1, v[176:177]
	v_lshl_add_u64 v[2:3], v[182:183], 0, v[2:3]
	v_lshl_add_u64 v[4:5], v[6:7], 0, v[178:179]
	v_lshl_add_u64 v[6:7], v[6:7], 0, v[180:181]
	global_load_dwordx4 v[10:13], v[2:3], off
	s_nop 0
	global_load_dwordx4 v[2:5], v[4:5], off
	global_load_dwordx4 v[6:9], v[6:7], off
	s_add_i32 s4, s48, s54
	s_cmp_lt_i32 s4, -1
	s_cbranch_scc1 .Lfd_entry
	v_add_u32_e32 v248, s0, v190
	ds_read_b128 v[196:199], v248 offset:9216
	ds_read_b128 v[200:203], v248 offset:13824
	ds_read_b128 v[204:207], v248 offset:18432
	ds_read_b128 v[208:211], v248 offset:23040
	ds_read_b128 v[212:215], v248 offset:9248
	ds_read_b128 v[216:219], v248 offset:13856
	ds_read_b128 v[220:223], v248 offset:18464
	ds_read_b128 v[224:227], v248 offset:23072
.LBB0_1072:
	s_add_i32 s57, s48, s54
	s_cmp_lt_i32 s57, 0
	s_cselect_b64 s[16:17], -1, 0
	s_add_i32 s56, s49, s47
	s_cmp_le_i32 s56, s46
	s_cselect_b64 s[4:5], -1, 0
	s_or_b64 s[18:19], s[16:17], s[4:5]
	s_mov_b32 s55, s51
	s_not_b64 s[4:5], s[18:19]
	s_andn2_b64 vcc, exec, s[18:19]
	s_mov_b32 s51, s0
	s_cbranch_vccnz .LBB0_1084
	s_cmp_lt_i32 s57, 0
	s_cbranch_scc0 .Ldiff_a_mask

.LBB0_1086:
	s_add_i32 s0, s54, 1
	s_cmp_lt_u32 s0, s44
	s_cselect_b64 s[0:1], -1, 0
	s_add_i32 s4, s56, 33
	s_cmp_le_i32 s4, s35
	s_cselect_b64 s[4:5], -1, 0
	s_or_b64 s[4:5], s[16:17], s[4:5]
	s_and_b64 s[0:1], s[0:1], s[4:5]
	s_andn2_b64 vcc, exec, s[0:1]
	v_add_u32_e32 v0, s55, v190
	s_cbranch_vccnz .LBB0_1088
	v_add_u32_e32 v248, s55, v190
	s_waitcnt lgkmcnt(4)
	v_mfma_f32_32x32x16_bf16 v[80:95], v[196:199], v[232:235], v[112:127]
	ds_read_b128 v[196:199], v248 offset:9216
	v_mfma_f32_32x32x16_bf16 v[96:111], v[200:203], v[232:235], v[112:127]
	ds_read_b128 v[200:203], v248 offset:13824
	v_mfma_f32_32x32x16_bf16 v[80:95], v[204:207], v[236:239], v[80:95]
	ds_read_b128 v[204:207], v248 offset:18432
	v_mfma_f32_32x32x16_bf16 v[96:111], v[208:211], v[236:239], v[96:111]
	ds_read_b128 v[208:211], v248 offset:23040
	s_waitcnt lgkmcnt(4)
	v_mfma_f32_32x32x16_bf16 v[80:95], v[212:215], v[240:243], v[80:95]
	ds_read_b128 v[212:215], v248 offset:9248
	v_mfma_f32_32x32x16_bf16 v[96:111], v[216:219], v[240:243], v[96:111]
	ds_read_b128 v[216:219], v248 offset:13856
	v_mfma_f32_32x32x16_bf16 v[80:95], v[220:223], v[244:247], v[80:95]
	ds_read_b128 v[220:223], v248 offset:18464
	v_mfma_f32_32x32x16_bf16 v[96:111], v[224:227], v[244:247], v[96:111]
	ds_read_b128 v[224:227], v248 offset:23072
.LBB0_1088:
	s_setprio 0
	s_add_i32 s0, s54, 4
	s_cmp_lt_u32 s54, s43
	s_cselect_b32 s0, s0, s45
	s_lshl_b32 s8, s0, 6
	v_add_u32_e32 v14, s8, v174
	v_ashrrev_i32_e32 v15, 31, v14
	v_lshlrev_b64 v[14:15], 10, v[14:15]
	v_lshl_add_u64 v[132:133], s[8:9], 1, v[176:177]
	v_lshl_add_u64 v[14:15], v[182:183], 0, v[14:15]
	v_lshl_add_u64 v[128:129], v[132:133], 0, v[178:179]
	global_load_dwordx4 v[136:139], v[14:15], off
	s_nop 0
	global_load_dwordx4 v[128:131], v[128:129], off
	v_lshl_add_u64 v[14:15], v[132:133], 0, v[180:181]
	global_load_dwordx4 v[132:135], v[14:15], off
	s_waitcnt lgkmcnt(8)
	s_barrier
	s_add_i32 s57, s57, 1
	s_cmp_lt_i32 s57, 0
	s_cselect_b64 s[0:1], -1, 0
	s_add_i32 s4, s56, 64
	s_cmp_le_i32 s4, s46
	s_cselect_b64 s[4:5], -1, 0
	s_or_b64 s[0:1], s[0:1], s[4:5]
	s_not_b64 s[4:5], s[0:1]
	s_andn2_b64 vcc, exec, s[0:1]
	s_cbranch_vccnz .LBB0_1094
	s_cmp_lt_i32 s57, 0
	s_cbranch_scc0 .Ldiff_b_mask

.LBB0_1096:
	s_add_i32 s54, s54, 2
	s_cmp_ge_u32 s54, s44
	s_cselect_b64 s[4:5], -1, 0
	s_cmp_lt_u32 s54, s44
	s_cselect_b64 s[0:1], -1, 0
	s_cmp_lt_i32 s57, -1
	s_cselect_b64 s[16:17], -1, 0
	s_addk_i32 s56, 0x61
	s_cmp_le_i32 s56, s35
	s_cselect_b64 s[18:19], -1, 0
	s_or_b64 s[16:17], s[16:17], s[18:19]
	s_and_b64 s[0:1], s[0:1], s[16:17]
	s_andn2_b64 vcc, exec, s[0:1]
	s_cbranch_vccnz .LBB0_1098
	v_add_u32_e32 v248, s50, v190
	s_waitcnt lgkmcnt(4)
	v_mfma_f32_32x32x16_bf16 v[80:95], v[196:199], v[232:235], v[112:127]
	ds_read_b128 v[196:199], v248 offset:9216
	v_mfma_f32_32x32x16_bf16 v[96:111], v[200:203], v[232:235], v[112:127]
	ds_read_b128 v[200:203], v248 offset:13824
	v_mfma_f32_32x32x16_bf16 v[80:95], v[204:207], v[236:239], v[80:95]
	ds_read_b128 v[204:207], v248 offset:18432
	v_mfma_f32_32x32x16_bf16 v[96:111], v[208:211], v[236:239], v[96:111]
	ds_read_b128 v[208:211], v248 offset:23040
	s_waitcnt lgkmcnt(4)
	v_mfma_f32_32x32x16_bf16 v[80:95], v[212:215], v[240:243], v[80:95]
	ds_read_b128 v[212:215], v248 offset:9248
	v_mfma_f32_32x32x16_bf16 v[96:111], v[216:219], v[240:243], v[96:111]
	ds_read_b128 v[216:219], v248 offset:13856
	v_mfma_f32_32x32x16_bf16 v[80:95], v[220:223], v[244:247], v[80:95]
	ds_read_b128 v[220:223], v248 offset:18464
	v_mfma_f32_32x32x16_bf16 v[96:111], v[224:227], v[244:247], v[96:111]
	ds_read_b128 v[224:227], v248 offset:23072

.Ldiff_b_nold:
	s_waitcnt lgkmcnt(8)
	s_barrier
	s_addk_i32 s47, 0x80
	s_and_b64 vcc, exec, s[4:5]
	s_cbranch_vccnz .LBB0_1100
	s_mov_b32 s0, s50
	s_mov_b32 s50, s55
	s_branch .LBB0_1072
